# peer_q GEMM loop: A tile loaded straight into its staging registers (no temp copy, no vmcnt(2) stall after the barrier)
# baseline (speedup 1.0000x reference)
.LBB0_427:
	ds_read_b128 v[128:131], v180
	ds_read_b128 v[132:135], v181 offset:36864
	ds_read_b128 v[136:139], v181 offset:41472
	s_waitcnt lgkmcnt(1)
	v_mfma_f32_32x32x16_bf16 v[48:63], v[128:131], v[132:135], v[48:63]
	s_waitcnt lgkmcnt(0)
	v_mfma_f32_32x32x16_bf16 v[32:47], v[128:131], v[136:139], v[32:47]
	ds_read_b128 v[128:131], v180 offset:4608
	s_waitcnt lgkmcnt(0)
	v_mfma_f32_32x32x16_bf16 v[16:31], v[128:131], v[132:135], v[16:31]
	v_mfma_f32_32x32x16_bf16 v[0:15], v[128:131], v[136:139], v[0:15]
	ds_read_b128 v[128:131], v180 offset:32
	ds_read_b128 v[132:135], v181 offset:36896
	ds_read_b128 v[136:139], v181 offset:41504
	s_waitcnt lgkmcnt(1)
	v_mfma_f32_32x32x16_bf16 v[48:63], v[128:131], v[132:135], v[48:63]
	s_waitcnt lgkmcnt(0)
	v_mfma_f32_32x32x16_bf16 v[32:47], v[128:131], v[136:139], v[32:47]
	ds_read_b128 v[128:131], v180 offset:4640
	s_waitcnt lgkmcnt(0)
	v_mfma_f32_32x32x16_bf16 v[16:31], v[128:131], v[132:135], v[16:31]
	v_mfma_f32_32x32x16_bf16 v[0:15], v[128:131], v[136:139], v[0:15]
	ds_read_b128 v[128:131], v180 offset:4672
	ds_read_b128 v[132:135], v181 offset:41536
	ds_read_b128 v[136:139], v181 offset:36928
	ds_read_b128 v[140:143], v181 offset:36960
	ds_read_b128 v[182:185], v180 offset:64
	ds_read_b128 v[186:189], v180 offset:96
	s_waitcnt lgkmcnt(4)
	v_mfma_f32_32x32x16_bf16 v[0:15], v[128:131], v[132:135], v[0:15]
	s_min_u32 s39, s38, 12
	s_add_i32 s39, s0, s39
	s_and_b32 s48, s39, 15
	s_waitcnt vmcnt(15)
	v_dot2c_f32_bf16_e32 v172, v84, v84
	s_waitcnt vmcnt(13)
	v_dot2c_f32_bf16_e32 v175, v116, v116
	s_waitcnt vmcnt(11)
	v_dot2c_f32_bf16_e32 v176, v120, v120
	s_waitcnt vmcnt(10)
	v_dot2c_f32_bf16_e32 v177, v124, v124
	s_waitcnt lgkmcnt(1)
	v_mfma_f32_32x32x16_bf16 v[48:63], v[182:185], v[136:139], v[48:63]
	v_dot2c_f32_bf16_e32 v172, v85, v85
	v_dot2c_f32_bf16_e32 v175, v117, v117
	v_dot2c_f32_bf16_e32 v176, v121, v121
	v_dot2c_f32_bf16_e32 v177, v125, v125
	v_dot2c_f32_bf16_e32 v172, v86, v86
	v_dot2c_f32_bf16_e32 v175, v118, v118
	v_dot2c_f32_bf16_e32 v176, v122, v122
	v_mfma_f32_32x32x16_bf16 v[32:47], v[182:185], v[132:135], v[32:47]
	v_dot2c_f32_bf16_e32 v177, v126, v126
	v_dot2c_f32_bf16_e32 v172, v87, v87
	v_dot2c_f32_bf16_e32 v175, v119, v119
	v_dot2c_f32_bf16_e32 v176, v123, v123
	v_dot2c_f32_bf16_e32 v177, v127, v127
	v_mfma_f32_32x32x16_bf16 v[16:31], v[128:131], v[136:139], v[16:31]
	ds_read_b128 v[128:131], v181 offset:41568
	ds_read_b128 v[132:135], v180 offset:4704
	ds_write_b128 v170, v[84:87] offset:18432
	s_waitcnt vmcnt(9)
	ds_write_b128 v170, v[64:67] offset:55296
	ds_write_b128 v171, v[116:119] offset:18432
	s_waitcnt vmcnt(8)
	ds_write_b128 v171, v[68:71] offset:55296
	ds_write_b128 v173, v[120:123] offset:18432
	s_waitcnt vmcnt(9)
	ds_write_b128 v173, v[72:75] offset:55296
	ds_write_b128 v174, v[124:127] offset:18432
	s_waitcnt vmcnt(8)
	ds_write_b128 v174, v[76:79] offset:55296
	s_lshl_b32 s48, s48, 7
	s_add_u32 s50, s98, s48
	s_addc_u32 s51, s99, 0
	s_add_u32 s48, s100, s48
	s_addc_u32 s49, s101, 0
	global_load_dwordx4 v[84:87], v250, s[50:51]
	global_load_dwordx4 v[64:67], v250, s[48:49]
	global_load_dwordx4 v[116:119], v251, s[50:51]
	global_load_dwordx4 v[68:71], v251, s[48:49]
	global_load_dwordx4 v[120:123], v252, s[50:51]
	global_load_dwordx4 v[124:127], v253, s[50:51]
	global_load_dwordx4 v[72:75], v252, s[48:49]
	global_load_dwordx4 v[76:79], v253, s[48:49]
	s_waitcnt lgkmcnt(10)
	v_mfma_f32_32x32x16_bf16 v[48:63], v[186:189], v[140:143], v[48:63]
	s_waitcnt lgkmcnt(9)
	v_mfma_f32_32x32x16_bf16 v[32:47], v[186:189], v[128:131], v[32:47]
	s_waitcnt lgkmcnt(8)
	v_mfma_f32_32x32x16_bf16 v[16:31], v[132:135], v[140:143], v[16:31]
	s_nop 0
	v_mfma_f32_32x32x16_bf16 v[0:15], v[132:135], v[128:131], v[0:15]
	s_nop 0
	s_waitcnt lgkmcnt(0)
	s_barrier
; #define GL_LOAD(KT_, S) { int kt_ = MID ? (((KT_) & 8) | (((KT_) + rot) & 7)) : (((KT_) + rot) & (KT - 1)); kt_ &= ktmask; asm volatile("" : "+s"(kt_)); GL_LD1(0, S) GL_LD1(1, S) GL_LD1(2, S) GL_LD1(3, S) }
; #define GL_STORE(BUF_, S, DOSSQ_) { const bool dossq_ = (DOSSQ_); GL_ST1(0, S, BUF_, ssq0) GL_ST1(1, S, BUF_, ssq1) GL_ST1(2, S, BUF_, ssq2) GL_ST1(3, S, BUF_, ssq3) }
; #define GL_RS(DEN_) { GL_RS1(0, ssq0, DEN_) GL_RS1(1, ssq1, DEN_) GL_RS1(2, ssq2, DEN_) GL_RS1(3, ssq3, DEN_) }
;     ...
;     for (int kt = 0; kt < KT; kt += 2) {
;       if (MID && kt == 8) {
;         GL_RS(512.f);
;         __syncthreads();
; #pragma unroll
;         for (int mi = 0; mi < 2; mi++) {
;           f32x16 sv;
; #pragma unroll
;           for (int r = 0; r < 16; r++) sv[r] = rs[64 * wm + 32 * mi + (r & 3) + 8 * (r >> 2) + 4 * lh];
;           acc[mi][0] *= sv; acc[mi][1] *= sv;
;         }
;       }
;       GL_COMPUTE(0);
;       GL_STORE(1, 1, !MID || (kt + 1) < 8);
;       GL_LOAD((kt + 3 < KT ? kt + 3 : KT - 1), 1);
;       __syncthreads();
;       GL_COMPUTE(1);
;       GL_STORE(0, 0, (kt + 2 < KT) && (!MID || (kt + 2) < 8));
;       GL_LOAD((kt + 4 < KT ? kt + 4 : KT - 1), 0);
;       __syncthreads();
;     }
;   }
;   if (!MID) GL_RS((float)K);
	ds_read_b128 v[182:185], v180 offset:23040
	ds_read_b128 v[186:189], v181 offset:59904
	ds_read_b128 v[190:193], v181 offset:55296
	ds_read_b128 v[194:197], v181 offset:55328
	ds_read_b128 v[198:201], v180 offset:18432
	ds_read_b128 v[202:205], v180 offset:18464
	s_waitcnt lgkmcnt(1)
	v_mfma_f32_32x32x16_bf16 v[48:63], v[198:201], v[190:193], v[48:63]
	v_mfma_f32_32x32x16_bf16 v[32:47], v[198:201], v[186:189], v[32:47]
	v_mfma_f32_32x32x16_bf16 v[16:31], v[182:185], v[190:193], v[16:31]
	v_mfma_f32_32x32x16_bf16 v[0:15], v[182:185], v[186:189], v[0:15]
	ds_read_b128 v[182:185], v181 offset:59936
	ds_read_b128 v[186:189], v180 offset:23072
	s_waitcnt lgkmcnt(2)
	v_mfma_f32_32x32x16_bf16 v[48:63], v[202:205], v[194:197], v[48:63]
	s_waitcnt lgkmcnt(1)
	v_mfma_f32_32x32x16_bf16 v[32:47], v[202:205], v[182:185], v[32:47]
	s_waitcnt lgkmcnt(0)
	v_mfma_f32_32x32x16_bf16 v[16:31], v[186:189], v[194:197], v[16:31]
	v_mfma_f32_32x32x16_bf16 v[0:15], v[186:189], v[182:185], v[0:15]
	ds_read_b128 v[182:185], v180 offset:23104
	ds_read_b128 v[186:189], v181 offset:59968
	ds_read_b128 v[190:193], v181 offset:55360
	ds_read_b128 v[194:197], v181 offset:55392
	ds_read_b128 v[198:201], v180 offset:18496
	ds_read_b128 v[202:205], v180 offset:18528
	s_waitcnt lgkmcnt(4)
	v_mfma_f32_32x32x16_bf16 v[0:15], v[182:185], v[186:189], v[0:15]
	s_min_u32 s48, s38, 11
	s_add_i32 s48, s1, s48
	s_and_b32 s48, s48, 15
	s_add_i32 s39, s38, 2
	s_waitcnt vmcnt(8)
	s_waitcnt lgkmcnt(1)
	v_mfma_f32_32x32x16_bf16 v[32:47], v[198:201], v[186:189], v[32:47]
	v_mfma_f32_32x32x16_bf16 v[16:31], v[182:185], v[190:193], v[16:31]
	ds_read_b128 v[182:185], v181 offset:60000
	ds_read_b128 v[186:189], v180 offset:23136
	ds_write_b128 v170, v[80:83]
	ds_write_b128 v170, v[108:111] offset:36864
	ds_write_b128 v171, v[96:99]
	ds_write_b128 v171, v[104:107] offset:36864
	ds_write_b128 v173, v[92:95]
	ds_write_b128 v173, v[100:103] offset:36864
	ds_write_b128 v174, v[88:91]
	ds_write_b128 v174, v[112:115] offset:36864
	s_lshl_b32 s48, s48, 7
	s_add_u32 s50, s98, s48
	s_addc_u32 s51, s99, 0
	s_add_u32 s48, s100, s48
	s_addc_u32 s49, s101, 0
	s_waitcnt lgkmcnt(9)
	v_mfma_f32_32x32x16_bf16 v[32:47], v[202:205], v[182:185], v[32:47]
	s_cmp_lt_u32 s38, 14
	s_waitcnt lgkmcnt(8)
	v_mfma_f32_32x32x16_bf16 v[0:15], v[186:189], v[182:185], v[0:15]
	v_mov_b32_e32 v184, v175
	v_mov_b32_e32 v185, v172
	v_mov_b32_e32 v182, v177
	v_mov_b32_e32 v175, v184
	v_mov_b32_e32 v183, v176
	v_dot2c_f32_bf16_e32 v175, v96, v96
	v_mov_b32_e32 v172, v185
	v_dot2c_f32_bf16_e32 v175, v97, v97
	v_mov_b32_e32 v177, v182
	v_dot2c_f32_bf16_e32 v172, v80, v80
	v_dot2c_f32_bf16_e32 v175, v98, v98
	v_mov_b32_e32 v176, v183
	v_dot2c_f32_bf16_e32 v177, v88, v88
	global_load_dwordx4 v[108:111], v250, s[48:49]
	v_dot2c_f32_bf16_e32 v172, v81, v81
	v_dot2c_f32_bf16_e32 v175, v99, v99
	v_dot2c_f32_bf16_e32 v176, v92, v92
	v_dot2c_f32_bf16_e32 v177, v89, v89
	global_load_dwordx4 v[96:99], v251, s[50:51]
	v_dot2c_f32_bf16_e32 v172, v82, v82
	v_dot2c_f32_bf16_e32 v176, v93, v93
	v_dot2c_f32_bf16_e32 v177, v90, v90
	global_load_dwordx4 v[104:107], v251, s[48:49]
	v_dot2c_f32_bf16_e32 v172, v83, v83
	v_dot2c_f32_bf16_e32 v176, v94, v94
	v_dot2c_f32_bf16_e32 v177, v91, v91
	global_load_dwordx4 v[80:83], v250, s[50:51]
	v_dot2c_f32_bf16_e32 v176, v95, v95
	global_load_dwordx4 v[88:91], v253, s[50:51]
	global_load_dwordx4 v[92:95], v252, s[50:51]
	global_load_dwordx4 v[112:115], v253, s[48:49]
	global_load_dwordx4 v[100:103], v252, s[48:49]
	v_mfma_f32_32x32x16_bf16 v[48:63], v[198:201], v[190:193], v[48:63]
	v_mfma_f32_32x32x16_bf16 v[48:63], v[202:205], v[194:197], v[48:63]
	s_mov_b32 s38, s39
	s_waitcnt lgkmcnt(0)
	s_barrier
	v_mfma_f32_32x32x16_bf16 v[16:31], v[186:189], v[194:197], v[16:31]
	s_cbranch_scc1 .LBB0_427
	s_waitcnt vmcnt(9)
	v_and_b32_e32 v65, 64, v162
	v_xor_b32_e32 v64, 1, v162
	v_add_u32_e32 v65, 64, v65
	v_cmp_lt_i32_e32 vcc, v64, v65
	v_xor_b32_e32 v67, 2, v162
	s_nop 0
	v_cndmask_b32_e32 v64, v162, v64, vcc
	v_lshlrev_b32_e32 v64, 2, v64
	ds_bpermute_b32 v66, v64, v185
	v_cmp_lt_i32_e32 vcc, v67, v65
	s_waitcnt lgkmcnt(0)
	v_add_f32_e32 v66, v185, v66
	v_cndmask_b32_e32 v67, v162, v67, vcc
	v_lshlrev_b32_e32 v67, 2, v67
	s_waitcnt vmcnt(8)
	ds_bpermute_b32 v68, v67, v66
	s_waitcnt lgkmcnt(0)
	v_add_f32_e32 v69, v66, v68
	v_xor_b32_e32 v66, 4, v162
	v_cmp_lt_i32_e32 vcc, v66, v65
	s_nop 1
	v_cndmask_b32_e32 v66, v162, v66, vcc
	v_lshlrev_b32_e32 v68, 2, v66
	ds_bpermute_b32 v70, v68, v69
	v_cmp_eq_u32_e32 vcc, 0, v168
	v_lshl_add_u32 v66, v169, 2, 16
	s_and_saveexec_b64 s[38:39], vcc
	s_cbranch_execz .LBB0_430
	s_waitcnt lgkmcnt(0)
	v_add_f32_e32 v69, v69, v70
	v_fmamk_f32 v69, v69, 0x3a800000, v164
	v_mul_f32_e32 v70, 0x4b800000, v69
	v_cmp_gt_f32_e64 s[0:1], s41, v69
	s_nop 1
	v_cndmask_b32_e64 v69, v69, v70, s[0:1]
	v_rsq_f32_e32 v69, v69
	s_nop 0
	v_mul_f32_e32 v70, 0x45800000, v69
	v_cndmask_b32_e64 v69, v69, v70, s[0:1]
	v_add_u32_e32 v70, 0x12000, v66
	ds_write_b32 v70, v69
